# reduce_slots phase and one grid barrier per layer removed: FFN13 epilogue sums the 32 row slots itself
# baseline (speedup 1.0000x reference)
; __device__ __forceinline__ unsigned char* opq(unsigned char* q) { asm volatile("" : "+s"(q)); return q; }
; __device__ __forceinline__ int opaque_tid() { int t = threadIdx.x; asm volatile("" : "+v"(t)); return t; }
; #define GBAR() do { XcdBarrier xb_; xb_.bar = (unsigned*)(opq(a.ws) + WS_BAR); xb_.x = xb_xcc_id(); xb_.st = (volatile LAS unsigned*)(lds + 131072); xcd_barrier(xb_); } while (0)
; __device__ __forceinline__ void reduce_slots(const float* slots, float* rsq) {
;     for (int row = blockIdx.x * 512 + opaque_tid(); row < M; row += gridDim.x * 512) {
;         const f32x4* s4 = (const f32x4*)(slots + (size_t)row * 32); float s = 0.f;
; #pragma unroll
;         for (int j = 0; j < 8; ++j) { const f32x4 v = s4[j]; s += (v[0] + v[1]) + (v[2] + v[3]); }
;         rsq[row] = s; }
; __global__ void __launch_bounds__(512, 2) mega_fwd(KArgs a) {
;     ...
;         GBAR();
;         reduce_slots((const float*)(opq(a.ws) + WS_SLOT) + (size_t)l * M * 32, (float*)(opq(a.ws) + WS_RSQ) + (size_t)l * M);
;         GBAR();
.LBB0_666:
	s_or_b64 exec, exec, s[40:41]
	s_mov_b64 s[8:9], s[68:69]
	s_mov_b64 s[10:11], s[68:69]
	v_mov_b32_e32 v0, v195
	s_waitcnt lgkmcnt(0)
	s_barrier
	s_branch .LBB0_713
	v_readlane_b32 s4, v253, 26
	s_nop 1
	v_add_u32_e32 v0, s4, v0
	s_mov_b32 s4, 0x8000
	v_cmp_gt_i32_e32 vcc, s4, v0
	s_and_saveexec_b64 s[6:7], vcc
	v_readlane_b32 s14, v253, 32
	s_movk_i32 s3, 0x90
	s_movk_i32 s2, 0x2a00
	v_readlane_b32 s15, v253, 33
	s_cbranch_execz .LBB0_669
	s_lshl_b64 s[4:5], s[38:39], 2
	s_add_u32 s4, s8, s4
	s_addc_u32 s5, s9, s5
	s_add_u32 s8, s4, 0x3e400000
	s_addc_u32 s9, s5, 0
	s_lshl_b64 s[4:5], s[78:79], 2
	s_add_u32 s4, s10, s4
	s_addc_u32 s5, s11, s5
	s_add_u32 s10, s4, 0x3e304000
	s_addc_u32 s11, s5, 0
	s_mov_b64 s[12:13], 0

; __device__ __forceinline__ float row_stat(const float* plain, const float* slots, int row, int fq) {
;     ...
;     const f32x4 a = *(const f32x4*)(slots + (size_t)row * 32 + fq * 8), b = *(const f32x4*)(slots + (size_t)row * 32 + fq * 8 + 4);
;     float s = ((a[0] + a[1]) + (a[2] + a[3])) + ((b[0] + b[1]) + (b[2] + b[3]));
;     s += __shfl_xor(s, 16); s += __shfl_xor(s, 32);
;     return s;
;     __device__ __forceinline__ void operator()(const f32x4 (&acc)[2][2][4][2], const Unit& u, int wr, int wc, int fr, int fq) const {
;     ...
;             for (int m = 0; m < 4; ++m) rsv[ai][m] = row_stat(rsq, slots, row0 + ai * HALF + m * 16, fq);
; #pragma unroll
;         for (int ai = 0; ai < 2; ++ai)
; #pragma unroll
;             for (int m = 0; m < 4; ++m) { bf16_t* rowp = H + (size_t)(row0 + ai * HALF + m * 16) * DFF;
;                 const float rs = rsqrtf(rsv[ai][m] * (1.f / DM) + EPS);
; #pragma unroll
;                 for (int bj = 0; bj < 2; ++bj) { const f32x4 a = acc[ai][bj][m][0] * rs, g = acc[ai][bj][m][1] * rs;
.LBB0_725:
	v_lshl_add_u32 v154, s43, 8, v138
	v_ashrrev_i32_e32 v155, 31, v154
	v_readlane_b32 s28, v255, 11
	v_bfe_u32 v244, v195, 4, 2
	v_lshlrev_b32_e32 v244, 5, v244
	v_lshl_add_u32 v244, v154, 7, v244
	v_mov_b32_e32 v245, 0
	v_mov_b32_e32 v242, s28
	v_lshlrev_b32_e32 v242, 22, v242
	v_add_u32_e32 v242, 0x3e400000, v242
	v_mov_b32_e32 v243, 0
	v_lshl_add_u64 v[242:243], s[68:69], 0, v[242:243]
	v_lshl_add_u64 v[242:243], v[242:243], 0, v[244:245]
	s_mov_b64 s[28:29], 0x1000
	v_lshl_add_u64 v[244:245], v[242:243], 0, s[28:29]
	s_mov_b64 s[28:29], 0x4000
	v_lshl_add_u64 v[246:247], v[242:243], 0, s[28:29]
	s_mov_b64 s[28:29], 0x5000
	v_lshl_add_u64 v[250:251], v[242:243], 0, s[28:29]
	global_load_dwordx4 v[164:167], v[242:243], off
	global_load_dwordx4 v[168:171], v[242:243], off offset:16
	global_load_dwordx4 v[172:175], v[242:243], off offset:2048
	global_load_dwordx4 v[176:179], v[242:243], off offset:2064
	global_load_dwordx4 v[180:183], v[244:245], off
	global_load_dwordx4 v[184:187], v[244:245], off offset:16
	global_load_dwordx4 v[188:191], v[244:245], off offset:2048
	global_load_dwordx4 v[202:205], v[244:245], off offset:2064
	global_load_dwordx4 v[206:209], v[246:247], off
	global_load_dwordx4 v[210:213], v[246:247], off offset:16
	global_load_dwordx4 v[214:217], v[246:247], off offset:2048
	global_load_dwordx4 v[218:221], v[246:247], off offset:2064
	global_load_dwordx4 v[222:225], v[250:251], off
	global_load_dwordx4 v[226:229], v[250:251], off offset:16
	global_load_dwordx4 v[230:233], v[250:251], off offset:2048
	global_load_dwordx4 v[196:199], v[250:251], off offset:2064
	v_or_b32_e32 v157, 16, v154
	v_mov_b64_e32 v[136:137], s[10:11]
	s_movk_i32 s0, 0x2c00
	v_or_b32_e32 v153, 32, v154
	v_or_b32_e32 v151, 48, v154
	v_add_u32_e32 v149, 0x80, v154
	v_add_u32_e32 v147, 0x90, v154
	v_add_u32_e32 v145, 0xa0, v154
	v_add_u32_e32 v143, 0xb0, v154
	v_mad_i64_i32 v[154:155], s[24:25], v154, s0, v[136:137]
	s_waitcnt vmcnt(0) lgkmcnt(0)
	v_add_f32_e32 v164, v164, v165
	v_add_f32_e32 v166, v166, v167
	v_add_f32_e32 v164, v164, v166
	v_add_f32_e32 v168, v168, v169
	v_add_f32_e32 v170, v170, v171
	v_add_f32_e32 v168, v168, v170
	v_add_f32_e32 v156, v164, v168
	v_add_f32_e32 v172, v172, v173
	v_add_f32_e32 v174, v174, v175
	v_add_f32_e32 v172, v172, v174
	v_add_f32_e32 v176, v176, v177
	v_add_f32_e32 v178, v178, v179
	v_add_f32_e32 v176, v176, v178
	v_add_f32_e32 v162, v172, v176
	v_add_f32_e32 v180, v180, v181
	v_add_f32_e32 v182, v182, v183
	v_add_f32_e32 v180, v180, v182
	v_add_f32_e32 v184, v184, v185
	v_add_f32_e32 v186, v186, v187
	v_add_f32_e32 v184, v184, v186
	v_add_f32_e32 v152, v180, v184
	v_add_f32_e32 v188, v188, v189
	v_add_f32_e32 v190, v190, v191
	v_add_f32_e32 v188, v188, v190
	v_add_f32_e32 v202, v202, v203
	v_add_f32_e32 v204, v204, v205
	v_add_f32_e32 v202, v202, v204
	v_add_f32_e32 v150, v188, v202
	v_add_f32_e32 v206, v206, v207
	v_add_f32_e32 v208, v208, v209
	v_add_f32_e32 v206, v206, v208
	v_add_f32_e32 v210, v210, v211
	v_add_f32_e32 v212, v212, v213
	v_add_f32_e32 v210, v210, v212
	v_add_f32_e32 v148, v206, v210
	v_add_f32_e32 v214, v214, v215
	v_add_f32_e32 v216, v216, v217
	v_add_f32_e32 v214, v214, v216
	v_add_f32_e32 v218, v218, v219
	v_add_f32_e32 v220, v220, v221
	v_add_f32_e32 v218, v218, v220
	v_add_f32_e32 v146, v214, v218
	v_add_f32_e32 v222, v222, v223
	v_add_f32_e32 v224, v224, v225
	v_add_f32_e32 v222, v222, v224
	v_add_f32_e32 v226, v226, v227
	v_add_f32_e32 v228, v228, v229
	v_add_f32_e32 v226, v226, v228
	v_add_f32_e32 v144, v222, v226
	v_add_f32_e32 v230, v230, v231
	v_add_f32_e32 v232, v232, v233
	v_add_f32_e32 v230, v230, v232
	v_add_f32_e32 v196, v196, v197
	v_add_f32_e32 v198, v198, v199
	v_add_f32_e32 v196, v196, v198
	v_add_f32_e32 v142, v230, v196
	ds_swizzle_b32 v164, v156 offset:0x401f
	ds_swizzle_b32 v172, v162 offset:0x401f
	ds_swizzle_b32 v180, v152 offset:0x401f
	ds_swizzle_b32 v188, v150 offset:0x401f
	ds_swizzle_b32 v206, v148 offset:0x401f
	ds_swizzle_b32 v214, v146 offset:0x401f
	ds_swizzle_b32 v222, v144 offset:0x401f
	ds_swizzle_b32 v230, v142 offset:0x401f
	s_waitcnt lgkmcnt(0)
	v_add_f32_e32 v156, v156, v164
	v_add_f32_e32 v162, v162, v172
	v_add_f32_e32 v152, v152, v180
	v_add_f32_e32 v150, v150, v188
	v_add_f32_e32 v148, v148, v206
	v_add_f32_e32 v146, v146, v214
	v_add_f32_e32 v144, v144, v222
	v_add_f32_e32 v142, v142, v230
	v_mov_b32_e32 v164, v156
	v_mov_b32_e32 v172, v162
	v_mov_b32_e32 v180, v152
	v_mov_b32_e32 v188, v150
	v_mov_b32_e32 v206, v148
	v_mov_b32_e32 v214, v146
	v_mov_b32_e32 v222, v144
	v_mov_b32_e32 v230, v142
	s_nop 1
	v_permlane32_swap_b32_e32 v156, v164
	v_permlane32_swap_b32_e32 v162, v172
	v_permlane32_swap_b32_e32 v152, v180
	v_permlane32_swap_b32_e32 v150, v188
	v_permlane32_swap_b32_e32 v148, v206
	v_permlane32_swap_b32_e32 v146, v214
	v_permlane32_swap_b32_e32 v144, v222
	v_permlane32_swap_b32_e32 v142, v230
	s_nop 1
	v_add_f32_e32 v156, v156, v164
	v_add_f32_e32 v162, v162, v172
	v_add_f32_e32 v152, v152, v180
	v_add_f32_e32 v150, v150, v188
	v_add_f32_e32 v148, v148, v206
	v_add_f32_e32 v146, v146, v214
	v_add_f32_e32 v144, v144, v222
	v_add_f32_e32 v142, v142, v230
	v_fmamk_f32 v156, v156, 0x3a000000, v194
	v_cmp_gt_f32_e32 vcc, s33, v156
	v_mul_f32_e32 v158, 0x4b800000, v156
	s_nop 0
	v_cndmask_b32_e32 v156, v156, v158, vcc
	v_rsq_f32_e32 v156, v156
	s_nop 0
	v_mul_f32_e32 v158, 0x45800000, v156
	v_cndmask_b32_e32 v156, v156, v158, vcc
	v_pk_mul_f32 v[126:127], v[126:127], v[156:157] op_sel_hi:[1,0]
	v_pk_mul_f32 v[122:123], v[122:123], v[156:157] op_sel_hi:[1,0]
	v_mul_f32_e32 v159, 0xbfb8aa3b, v126
	v_exp_f32_e32 v159, v159
; __device__ __forceinline__ unsigned cvt_pk_bf16(float lo, float hi) { f32x2 v = {lo, hi}; bf16x2_t b = __builtin_convertvector(v, bf16x2_t); return __builtin_bit_cast(unsigned, b); }
; __device__ __forceinline__ float silu_(float z) { return z * sigmoid_(z); }
;     __device__ __forceinline__ void operator()(const f32x4 (&acc)[2][2][4][2], const Unit& u, int wr, int wc, int fr, int fq) const {
;     ...
;             for (int m = 0; m < 4; ++m) { bf16_t* rowp = H + (size_t)(row0 + ai * HALF + m * 16) * DFF;
;                 const float rs = rsqrtf(rsv[ai][m] * (1.f / DM) + EPS);
; #pragma unroll
;                 for (int bj = 0; bj < 2; ++bj) { const f32x4 a = acc[ai][bj][m][0] * rs, g = acc[ai][bj][m][1] * rs;
;                     const int col = 16 * (8 * u.pn + 4 * bj + wc) + 4 * fq;
;                     u32x2 w; w.x = cvt_pk_bf16(silu_(a[0]) * g[0], silu_(a[1]) * g[1]); w.y = cvt_pk_bf16(silu_(a[2]) * g[2], silu_(a[3]) * g[3]);
;                     *(u32x2*)(rowp + col) = w; } }
	v_pk_mul_f32 v[128:129], v[128:129], v[156:157] op_sel_hi:[1,0]
	v_pk_mul_f32 v[124:125], v[124:125], v[156:157] op_sel_hi:[1,0]
	v_lshl_or_b32 v158, s42, 7, v140
	v_add_f32_e32 v159, 1.0, v159
	v_rcp_f32_e32 v160, v159
	v_mul_f32_e32 v159, 0xbfb8aa3b, v127
	v_exp_f32_e32 v159, v159
	v_pk_mul_f32 v[118:119], v[118:119], v[156:157] op_sel_hi:[1,0]
	v_pk_mul_f32 v[114:115], v[114:115], v[156:157] op_sel_hi:[1,0]
	v_pk_mul_f32 v[120:121], v[120:121], v[156:157] op_sel_hi:[1,0]
	v_add_f32_e32 v159, 1.0, v159
	v_rcp_f32_e32 v161, v159
	v_ashrrev_i32_e32 v159, 31, v158
	v_pk_mul_f32 v[116:117], v[116:117], v[156:157] op_sel_hi:[1,0]
	v_pk_mul_f32 v[126:127], v[126:127], v[160:161]
	s_nop 0
	v_pk_mul_f32 v[122:123], v[122:123], v[126:127]
	s_nop 0
	v_cvt_pk_bf16_f32 v126, v122, v123
	v_mul_f32_e32 v122, 0xbfb8aa3b, v128
	v_mul_f32_e32 v123, 0xbfb8aa3b, v129
	v_exp_f32_e32 v122, v122
	v_exp_f32_e32 v123, v123
	v_add_f32_e32 v122, 1.0, v122
	v_add_f32_e32 v123, 1.0, v123
	v_rcp_f32_e32 v122, v122
	v_rcp_f32_e32 v123, v123
	s_nop 0
	v_pk_mul_f32 v[122:123], v[128:129], v[122:123]
	s_nop 0
	v_pk_mul_f32 v[122:123], v[124:125], v[122:123]
	s_nop 0
	v_cvt_pk_bf16_f32 v127, v122, v123
	v_lshlrev_b64 v[122:123], 1, v[158:159]
	v_lshl_add_u64 v[124:125], v[154:155], 0, v[122:123]
	global_store_dwordx2 v[124:125], v[126:127], off
	v_mul_f32_e32 v126, 0xbfb8aa3b, v118
	v_mul_f32_e32 v127, 0xbfb8aa3b, v119
	v_exp_f32_e32 v126, v126
	v_exp_f32_e32 v127, v127
	v_add_f32_e32 v126, 1.0, v126
	v_add_f32_e32 v127, 1.0, v127
	v_rcp_f32_e32 v126, v126
	v_rcp_f32_e32 v127, v127
	s_nop 0
	v_pk_mul_f32 v[118:119], v[118:119], v[126:127]
	s_nop 0
	v_pk_mul_f32 v[114:115], v[114:115], v[118:119]
	s_nop 0
	v_cvt_pk_bf16_f32 v114, v114, v115
	v_mul_f32_e32 v115, 0xbfb8aa3b, v120
	v_exp_f32_e32 v115, v115
	s_nop 0
	v_add_f32_e32 v115, 1.0, v115
	v_rcp_f32_e32 v118, v115
	v_mul_f32_e32 v115, 0xbfb8aa3b, v121
	v_exp_f32_e32 v115, v115
	s_nop 0
	v_add_f32_e32 v115, 1.0, v115
	v_rcp_f32_e32 v119, v115
	s_nop 0
	v_pk_mul_f32 v[118:119], v[120:121], v[118:119]
	s_nop 0
	v_pk_mul_f32 v[116:117], v[116:117], v[118:119]
	s_nop 0
	v_cvt_pk_bf16_f32 v115, v116, v117
	v_fmamk_f32 v116, v162, 0x3a000000, v194
	v_cmp_gt_f32_e32 vcc, s33, v116
	v_mul_f32_e32 v117, 0x4b800000, v116
	global_store_dwordx2 v[124:125], v[114:115], off offset:128
	v_cndmask_b32_e32 v116, v116, v117, vcc
	v_rsq_f32_e32 v116, v116
	v_mad_i64_i32 v[114:115], s[24:25], v157, s0, v[136:137]
	v_mul_f32_e32 v117, 0x45800000, v116
	v_cndmask_b32_e32 v116, v116, v117, vcc
	v_pk_mul_f32 v[108:109], v[108:109], v[116:117] op_sel_hi:[1,0]
	v_pk_mul_f32 v[110:111], v[110:111], v[116:117] op_sel_hi:[1,0]
	v_pk_mul_f32 v[106:107], v[106:107], v[116:117] op_sel_hi:[1,0]
	v_pk_mul_f32 v[104:105], v[104:105], v[116:117] op_sel_hi:[1,0]
	v_mul_f32_e32 v117, 0xbfb8aa3b, v108
	v_exp_f32_e32 v117, v117
	s_nop 0
	v_add_f32_e32 v117, 1.0, v117
	v_rcp_f32_e32 v118, v117
	v_mul_f32_e32 v117, 0xbfb8aa3b, v109
	v_exp_f32_e32 v117, v117
	s_nop 0
	v_add_f32_e32 v117, 1.0, v117
	v_rcp_f32_e32 v119, v117
	v_pk_mul_f32 v[100:101], v[100:101], v[116:117] op_sel_hi:[1,0]
	v_pk_mul_f32 v[96:97], v[96:97], v[116:117] op_sel_hi:[1,0]
	v_pk_mul_f32 v[102:103], v[102:103], v[116:117] op_sel_hi:[1,0]
	v_pk_mul_f32 v[108:109], v[108:109], v[118:119]
	v_pk_mul_f32 v[98:99], v[98:99], v[116:117] op_sel_hi:[1,0]
	v_pk_mul_f32 v[104:105], v[104:105], v[108:109]
	s_nop 0
	v_cvt_pk_bf16_f32 v104, v104, v105
	v_mul_f32_e32 v105, 0xbfb8aa3b, v110
	v_exp_f32_e32 v105, v105
	s_nop 0
	v_add_f32_e32 v105, 1.0, v105
	v_rcp_f32_e32 v108, v105
	v_mul_f32_e32 v105, 0xbfb8aa3b, v111
	v_exp_f32_e32 v105, v105
	s_nop 0
	v_add_f32_e32 v105, 1.0, v105
	v_rcp_f32_e32 v109, v105
	s_nop 0
	v_pk_mul_f32 v[108:109], v[110:111], v[108:109]
	s_nop 0
	v_pk_mul_f32 v[106:107], v[106:107], v[108:109]
	s_nop 0
	v_cvt_pk_bf16_f32 v105, v106, v107
	v_lshl_add_u64 v[106:107], v[114:115], 0, v[122:123]
	global_store_dwordx2 v[106:107], v[104:105], off
	v_mul_f32_e32 v104, 0xbfb8aa3b, v100
	v_mul_f32_e32 v105, 0xbfb8aa3b, v101
	v_exp_f32_e32 v104, v104
	v_exp_f32_e32 v105, v105
	v_add_f32_e32 v104, 1.0, v104
	v_add_f32_e32 v105, 1.0, v105
	v_rcp_f32_e32 v104, v104
	v_rcp_f32_e32 v105, v105
	s_nop 0
	v_pk_mul_f32 v[100:101], v[100:101], v[104:105]
	s_nop 0
	v_pk_mul_f32 v[96:97], v[96:97], v[100:101]
	s_nop 0
	v_cvt_pk_bf16_f32 v96, v96, v97
	v_mul_f32_e32 v97, 0xbfb8aa3b, v102
	v_exp_f32_e32 v97, v97
	s_nop 0
	v_add_f32_e32 v97, 1.0, v97
	v_rcp_f32_e32 v100, v97
	v_mul_f32_e32 v97, 0xbfb8aa3b, v103
	v_exp_f32_e32 v97, v97
	s_nop 0
	v_add_f32_e32 v97, 1.0, v97
	v_rcp_f32_e32 v101, v97
	s_nop 0
	v_pk_mul_f32 v[100:101], v[102:103], v[100:101]
	s_nop 0
	v_pk_mul_f32 v[98:99], v[98:99], v[100:101]
	s_nop 0
	v_cvt_pk_bf16_f32 v97, v98, v99
	v_fmamk_f32 v98, v152, 0x3a000000, v194
	v_cmp_gt_f32_e32 vcc, s33, v98
	v_mul_f32_e32 v99, 0x4b800000, v98
	global_store_dwordx2 v[106:107], v[96:97], off offset:128
	v_cndmask_b32_e32 v98, v98, v99, vcc
	v_rsq_f32_e32 v98, v98
	v_mad_i64_i32 v[96:97], s[24:25], v153, s0, v[136:137]
	v_mul_f32_e32 v99, 0x45800000, v98
	v_cndmask_b32_e32 v98, v98, v99, vcc
	v_pk_mul_f32 v[92:93], v[92:93], v[98:99] op_sel_hi:[1,0]
	v_pk_mul_f32 v[94:95], v[94:95], v[98:99] op_sel_hi:[1,0]
	v_pk_mul_f32 v[90:91], v[90:91], v[98:99] op_sel_hi:[1,0]
	v_pk_mul_f32 v[88:89], v[88:89], v[98:99] op_sel_hi:[1,0]
	v_mul_f32_e32 v99, 0xbfb8aa3b, v92
	v_exp_f32_e32 v99, v99
	s_nop 0
	v_add_f32_e32 v99, 1.0, v99
	v_rcp_f32_e32 v100, v99
	v_mul_f32_e32 v99, 0xbfb8aa3b, v93
	v_exp_f32_e32 v99, v99
	s_nop 0
	v_add_f32_e32 v99, 1.0, v99
	v_rcp_f32_e32 v101, v99
; __device__ __forceinline__ unsigned cvt_pk_bf16(float lo, float hi) { f32x2 v = {lo, hi}; bf16x2_t b = __builtin_convertvector(v, bf16x2_t); return __builtin_bit_cast(unsigned, b); }
; __device__ __forceinline__ float silu_(float z) { return z * sigmoid_(z); }
;     __device__ __forceinline__ void operator()(const f32x4 (&acc)[2][2][4][2], const Unit& u, int wr, int wc, int fr, int fq) const {
;     ...
;             for (int m = 0; m < 4; ++m) { bf16_t* rowp = H + (size_t)(row0 + ai * HALF + m * 16) * DFF;
;                 const float rs = rsqrtf(rsv[ai][m] * (1.f / DM) + EPS);
; #pragma unroll
;                 for (int bj = 0; bj < 2; ++bj) { const f32x4 a = acc[ai][bj][m][0] * rs, g = acc[ai][bj][m][1] * rs;
;                     const int col = 16 * (8 * u.pn + 4 * bj + wc) + 4 * fq;
;                     u32x2 w; w.x = cvt_pk_bf16(silu_(a[0]) * g[0], silu_(a[1]) * g[1]); w.y = cvt_pk_bf16(silu_(a[2]) * g[2], silu_(a[3]) * g[3]);
;                     *(u32x2*)(rowp + col) = w; } }
	v_pk_mul_f32 v[84:85], v[84:85], v[98:99] op_sel_hi:[1,0]
	v_pk_mul_f32 v[80:81], v[80:81], v[98:99] op_sel_hi:[1,0]
	v_pk_mul_f32 v[86:87], v[86:87], v[98:99] op_sel_hi:[1,0]
	v_pk_mul_f32 v[92:93], v[92:93], v[100:101]
	v_pk_mul_f32 v[82:83], v[82:83], v[98:99] op_sel_hi:[1,0]
	v_pk_mul_f32 v[88:89], v[88:89], v[92:93]
	s_nop 0
	v_cvt_pk_bf16_f32 v88, v88, v89
	v_mul_f32_e32 v89, 0xbfb8aa3b, v94
	v_exp_f32_e32 v89, v89
	s_nop 0
	v_add_f32_e32 v89, 1.0, v89
	v_rcp_f32_e32 v92, v89
	v_mul_f32_e32 v89, 0xbfb8aa3b, v95
	v_exp_f32_e32 v89, v89
	s_nop 0
	v_add_f32_e32 v89, 1.0, v89
	v_rcp_f32_e32 v93, v89
	s_nop 0
	v_pk_mul_f32 v[92:93], v[94:95], v[92:93]
	s_nop 0
	v_pk_mul_f32 v[90:91], v[90:91], v[92:93]
	s_nop 0
	v_cvt_pk_bf16_f32 v89, v90, v91
	v_lshl_add_u64 v[90:91], v[96:97], 0, v[122:123]
	global_store_dwordx2 v[90:91], v[88:89], off
	v_mul_f32_e32 v88, 0xbfb8aa3b, v84
	v_mul_f32_e32 v89, 0xbfb8aa3b, v85
	v_exp_f32_e32 v88, v88
	v_exp_f32_e32 v89, v89
	v_add_f32_e32 v88, 1.0, v88
	v_add_f32_e32 v89, 1.0, v89
	v_rcp_f32_e32 v88, v88
	v_rcp_f32_e32 v89, v89
	s_nop 0
	v_pk_mul_f32 v[84:85], v[84:85], v[88:89]
	s_nop 0
	v_pk_mul_f32 v[80:81], v[80:81], v[84:85]
	s_nop 0
	v_cvt_pk_bf16_f32 v80, v80, v81
	v_mul_f32_e32 v81, 0xbfb8aa3b, v86
	v_exp_f32_e32 v81, v81
	s_nop 0
	v_add_f32_e32 v81, 1.0, v81
	v_rcp_f32_e32 v84, v81
	v_mul_f32_e32 v81, 0xbfb8aa3b, v87
	v_exp_f32_e32 v81, v81
	s_nop 0
	v_add_f32_e32 v81, 1.0, v81
	v_rcp_f32_e32 v85, v81
	s_nop 0
	v_pk_mul_f32 v[84:85], v[86:87], v[84:85]
	s_nop 0
	v_pk_mul_f32 v[82:83], v[82:83], v[84:85]
	s_nop 0
	v_cvt_pk_bf16_f32 v81, v82, v83
	v_fmamk_f32 v82, v150, 0x3a000000, v194
	v_cmp_gt_f32_e32 vcc, s33, v82
	v_mul_f32_e32 v83, 0x4b800000, v82
	global_store_dwordx2 v[90:91], v[80:81], off offset:128
	v_cndmask_b32_e32 v82, v82, v83, vcc
	v_rsq_f32_e32 v82, v82
	v_mad_i64_i32 v[80:81], s[24:25], v151, s0, v[136:137]
	v_mul_f32_e32 v83, 0x45800000, v82
	v_cndmask_b32_e32 v82, v82, v83, vcc
	v_pk_mul_f32 v[76:77], v[76:77], v[82:83] op_sel_hi:[1,0]
	v_pk_mul_f32 v[78:79], v[78:79], v[82:83] op_sel_hi:[1,0]
	v_pk_mul_f32 v[74:75], v[74:75], v[82:83] op_sel_hi:[1,0]
	v_pk_mul_f32 v[72:73], v[72:73], v[82:83] op_sel_hi:[1,0]
	v_mul_f32_e32 v83, 0xbfb8aa3b, v76
	v_exp_f32_e32 v83, v83
	s_nop 0
	v_add_f32_e32 v83, 1.0, v83
	v_rcp_f32_e32 v84, v83
	v_mul_f32_e32 v83, 0xbfb8aa3b, v77
	v_exp_f32_e32 v83, v83
	s_nop 0
	v_add_f32_e32 v83, 1.0, v83
	v_rcp_f32_e32 v85, v83
	v_pk_mul_f32 v[68:69], v[68:69], v[82:83] op_sel_hi:[1,0]
	v_pk_mul_f32 v[64:65], v[64:65], v[82:83] op_sel_hi:[1,0]
	v_pk_mul_f32 v[70:71], v[70:71], v[82:83] op_sel_hi:[1,0]
	v_pk_mul_f32 v[76:77], v[76:77], v[84:85]
	v_pk_mul_f32 v[66:67], v[66:67], v[82:83] op_sel_hi:[1,0]
	v_pk_mul_f32 v[72:73], v[72:73], v[76:77]
	s_nop 0
	v_cvt_pk_bf16_f32 v72, v72, v73
	v_mul_f32_e32 v73, 0xbfb8aa3b, v78
	v_exp_f32_e32 v73, v73
	s_nop 0
	v_add_f32_e32 v73, 1.0, v73
	v_rcp_f32_e32 v76, v73
	v_mul_f32_e32 v73, 0xbfb8aa3b, v79
	v_exp_f32_e32 v73, v73
	s_nop 0
	v_add_f32_e32 v73, 1.0, v73
	v_rcp_f32_e32 v77, v73
	s_nop 0
	v_pk_mul_f32 v[76:77], v[78:79], v[76:77]
	s_nop 0
	v_pk_mul_f32 v[74:75], v[74:75], v[76:77]
	s_nop 0
	v_cvt_pk_bf16_f32 v73, v74, v75
	v_lshl_add_u64 v[74:75], v[80:81], 0, v[122:123]
	global_store_dwordx2 v[74:75], v[72:73], off
	v_mul_f32_e32 v72, 0xbfb8aa3b, v68
	v_mul_f32_e32 v73, 0xbfb8aa3b, v69
	v_exp_f32_e32 v72, v72
	v_exp_f32_e32 v73, v73
	v_add_f32_e32 v72, 1.0, v72
	v_add_f32_e32 v73, 1.0, v73
	v_rcp_f32_e32 v72, v72
	v_rcp_f32_e32 v73, v73
	s_nop 0
	v_pk_mul_f32 v[68:69], v[68:69], v[72:73]
	s_nop 0
	v_pk_mul_f32 v[64:65], v[64:65], v[68:69]
	s_nop 0
	v_cvt_pk_bf16_f32 v64, v64, v65
	v_mul_f32_e32 v65, 0xbfb8aa3b, v70
	v_exp_f32_e32 v65, v65
	s_nop 0
	v_add_f32_e32 v65, 1.0, v65
	v_rcp_f32_e32 v68, v65
	v_mul_f32_e32 v65, 0xbfb8aa3b, v71
	v_exp_f32_e32 v65, v65
	s_nop 0
	v_add_f32_e32 v65, 1.0, v65
	v_rcp_f32_e32 v69, v65
	s_nop 0
	v_pk_mul_f32 v[68:69], v[70:71], v[68:69]
	s_nop 0
	v_pk_mul_f32 v[66:67], v[66:67], v[68:69]
	s_nop 0
	v_cvt_pk_bf16_f32 v65, v66, v67
	v_fmamk_f32 v66, v148, 0x3a000000, v194
	v_cmp_gt_f32_e32 vcc, s33, v66
	v_mul_f32_e32 v67, 0x4b800000, v66
	global_store_dwordx2 v[74:75], v[64:65], off offset:128
	v_cndmask_b32_e32 v66, v66, v67, vcc
	v_rsq_f32_e32 v66, v66
	v_mad_i64_i32 v[64:65], s[24:25], v149, s0, v[136:137]
	v_mul_f32_e32 v67, 0x45800000, v66
	v_cndmask_b32_e32 v66, v66, v67, vcc
	v_pk_mul_f32 v[60:61], v[60:61], v[66:67] op_sel_hi:[1,0]
	v_pk_mul_f32 v[62:63], v[62:63], v[66:67] op_sel_hi:[1,0]
	v_pk_mul_f32 v[58:59], v[58:59], v[66:67] op_sel_hi:[1,0]
	v_pk_mul_f32 v[56:57], v[56:57], v[66:67] op_sel_hi:[1,0]
	v_mul_f32_e32 v67, 0xbfb8aa3b, v60
	v_exp_f32_e32 v67, v67
	s_nop 0
	v_add_f32_e32 v67, 1.0, v67
	v_rcp_f32_e32 v68, v67
	v_mul_f32_e32 v67, 0xbfb8aa3b, v61
	v_exp_f32_e32 v67, v67
	s_nop 0
	v_add_f32_e32 v67, 1.0, v67
	v_rcp_f32_e32 v69, v67
	v_pk_mul_f32 v[52:53], v[52:53], v[66:67] op_sel_hi:[1,0]
	v_pk_mul_f32 v[48:49], v[48:49], v[66:67] op_sel_hi:[1,0]
	v_pk_mul_f32 v[54:55], v[54:55], v[66:67] op_sel_hi:[1,0]
	v_pk_mul_f32 v[60:61], v[60:61], v[68:69]
	v_pk_mul_f32 v[50:51], v[50:51], v[66:67] op_sel_hi:[1,0]
	v_pk_mul_f32 v[56:57], v[56:57], v[60:61]
	s_nop 0
	v_cvt_pk_bf16_f32 v56, v56, v57
	v_mul_f32_e32 v57, 0xbfb8aa3b, v62
	v_exp_f32_e32 v57, v57
	s_nop 0
	v_add_f32_e32 v57, 1.0, v57
	v_rcp_f32_e32 v60, v57
	v_mul_f32_e32 v57, 0xbfb8aa3b, v63
	v_exp_f32_e32 v57, v57
	s_nop 0
	v_add_f32_e32 v57, 1.0, v57
	v_rcp_f32_e32 v61, v57
	s_nop 0
	v_pk_mul_f32 v[60:61], v[62:63], v[60:61]
	s_nop 0
	v_pk_mul_f32 v[58:59], v[58:59], v[60:61]
	s_nop 0
	v_cvt_pk_bf16_f32 v57, v58, v59
; __device__ __forceinline__ unsigned cvt_pk_bf16(float lo, float hi) { f32x2 v = {lo, hi}; bf16x2_t b = __builtin_convertvector(v, bf16x2_t); return __builtin_bit_cast(unsigned, b); }
; __device__ __forceinline__ float silu_(float z) { return z * sigmoid_(z); }
;     __device__ __forceinline__ void operator()(const f32x4 (&acc)[2][2][4][2], const Unit& u, int wr, int wc, int fr, int fq) const {
;     ...
;             for (int m = 0; m < 4; ++m) { bf16_t* rowp = H + (size_t)(row0 + ai * HALF + m * 16) * DFF;
;                 const float rs = rsqrtf(rsv[ai][m] * (1.f / DM) + EPS);
; #pragma unroll
;                 for (int bj = 0; bj < 2; ++bj) { const f32x4 a = acc[ai][bj][m][0] * rs, g = acc[ai][bj][m][1] * rs;
;                     const int col = 16 * (8 * u.pn + 4 * bj + wc) + 4 * fq;
;                     u32x2 w; w.x = cvt_pk_bf16(silu_(a[0]) * g[0], silu_(a[1]) * g[1]); w.y = cvt_pk_bf16(silu_(a[2]) * g[2], silu_(a[3]) * g[3]);
;                     *(u32x2*)(rowp + col) = w; } }
	v_lshl_add_u64 v[58:59], v[64:65], 0, v[122:123]
	global_store_dwordx2 v[58:59], v[56:57], off
	v_mul_f32_e32 v56, 0xbfb8aa3b, v52
	v_mul_f32_e32 v57, 0xbfb8aa3b, v53
	v_exp_f32_e32 v56, v56
	v_exp_f32_e32 v57, v57
	v_add_f32_e32 v56, 1.0, v56
	v_add_f32_e32 v57, 1.0, v57
	v_rcp_f32_e32 v56, v56
	v_rcp_f32_e32 v57, v57
	s_nop 0
	v_pk_mul_f32 v[52:53], v[52:53], v[56:57]
	s_nop 0
	v_pk_mul_f32 v[48:49], v[48:49], v[52:53]
	s_nop 0
	v_cvt_pk_bf16_f32 v48, v48, v49
	v_mul_f32_e32 v49, 0xbfb8aa3b, v54
	v_exp_f32_e32 v49, v49
	s_nop 0
	v_add_f32_e32 v49, 1.0, v49
	v_rcp_f32_e32 v52, v49
	v_mul_f32_e32 v49, 0xbfb8aa3b, v55
	v_exp_f32_e32 v49, v49
	s_nop 0
	v_add_f32_e32 v49, 1.0, v49
	v_rcp_f32_e32 v53, v49
	s_nop 0
	v_pk_mul_f32 v[52:53], v[54:55], v[52:53]
	s_nop 0
	v_pk_mul_f32 v[50:51], v[50:51], v[52:53]
	s_nop 0
	v_cvt_pk_bf16_f32 v49, v50, v51
	v_fmamk_f32 v50, v146, 0x3a000000, v194
	v_cmp_gt_f32_e32 vcc, s33, v50
	v_mul_f32_e32 v51, 0x4b800000, v50
	global_store_dwordx2 v[58:59], v[48:49], off offset:128
	v_cndmask_b32_e32 v50, v50, v51, vcc
	v_rsq_f32_e32 v50, v50
	v_mad_i64_i32 v[48:49], s[24:25], v147, s0, v[136:137]
	v_mul_f32_e32 v51, 0x45800000, v50
	v_cndmask_b32_e32 v50, v50, v51, vcc
	v_pk_mul_f32 v[44:45], v[44:45], v[50:51] op_sel_hi:[1,0]
	v_pk_mul_f32 v[46:47], v[46:47], v[50:51] op_sel_hi:[1,0]
	v_pk_mul_f32 v[42:43], v[42:43], v[50:51] op_sel_hi:[1,0]
	v_pk_mul_f32 v[40:41], v[40:41], v[50:51] op_sel_hi:[1,0]
	v_mul_f32_e32 v51, 0xbfb8aa3b, v44
	v_exp_f32_e32 v51, v51
	s_nop 0
	v_add_f32_e32 v51, 1.0, v51
	v_rcp_f32_e32 v52, v51
	v_mul_f32_e32 v51, 0xbfb8aa3b, v45
	v_exp_f32_e32 v51, v51
	s_nop 0
	v_add_f32_e32 v51, 1.0, v51
	v_rcp_f32_e32 v53, v51
	v_pk_mul_f32 v[36:37], v[36:37], v[50:51] op_sel_hi:[1,0]
	v_pk_mul_f32 v[32:33], v[32:33], v[50:51] op_sel_hi:[1,0]
	v_pk_mul_f32 v[38:39], v[38:39], v[50:51] op_sel_hi:[1,0]
	v_pk_mul_f32 v[44:45], v[44:45], v[52:53]
	v_pk_mul_f32 v[34:35], v[34:35], v[50:51] op_sel_hi:[1,0]
	v_pk_mul_f32 v[40:41], v[40:41], v[44:45]
	s_nop 0
	v_cvt_pk_bf16_f32 v40, v40, v41
	v_mul_f32_e32 v41, 0xbfb8aa3b, v46
	v_exp_f32_e32 v41, v41
	s_nop 0
	v_add_f32_e32 v41, 1.0, v41
	v_rcp_f32_e32 v44, v41
	v_mul_f32_e32 v41, 0xbfb8aa3b, v47
	v_exp_f32_e32 v41, v41
	s_nop 0
	v_add_f32_e32 v41, 1.0, v41
	v_rcp_f32_e32 v45, v41
	s_nop 0
	v_pk_mul_f32 v[44:45], v[46:47], v[44:45]
	s_nop 0
	v_pk_mul_f32 v[42:43], v[42:43], v[44:45]
	s_nop 0
	v_cvt_pk_bf16_f32 v41, v42, v43
	v_lshl_add_u64 v[42:43], v[48:49], 0, v[122:123]
	global_store_dwordx2 v[42:43], v[40:41], off
	v_mul_f32_e32 v40, 0xbfb8aa3b, v36
	v_mul_f32_e32 v41, 0xbfb8aa3b, v37
	v_exp_f32_e32 v40, v40
	v_exp_f32_e32 v41, v41
	v_add_f32_e32 v40, 1.0, v40
	v_add_f32_e32 v41, 1.0, v41
	v_rcp_f32_e32 v40, v40
	v_rcp_f32_e32 v41, v41
	s_nop 0
	v_pk_mul_f32 v[36:37], v[36:37], v[40:41]
	s_nop 0
	v_pk_mul_f32 v[32:33], v[32:33], v[36:37]
	s_nop 0
	v_cvt_pk_bf16_f32 v32, v32, v33
	v_mul_f32_e32 v33, 0xbfb8aa3b, v38
	v_exp_f32_e32 v33, v33
	s_nop 0
	v_add_f32_e32 v33, 1.0, v33
	v_rcp_f32_e32 v36, v33
	v_mul_f32_e32 v33, 0xbfb8aa3b, v39
	v_exp_f32_e32 v33, v33
	s_nop 0
	v_add_f32_e32 v33, 1.0, v33
	v_rcp_f32_e32 v37, v33
	s_nop 0
	v_pk_mul_f32 v[36:37], v[38:39], v[36:37]
	s_nop 0
	v_pk_mul_f32 v[34:35], v[34:35], v[36:37]
	s_nop 0
	v_cvt_pk_bf16_f32 v33, v34, v35
	v_fmamk_f32 v34, v144, 0x3a000000, v194
	v_cmp_gt_f32_e32 vcc, s33, v34
	v_mul_f32_e32 v35, 0x4b800000, v34
	global_store_dwordx2 v[42:43], v[32:33], off offset:128
	v_cndmask_b32_e32 v34, v34, v35, vcc
	v_rsq_f32_e32 v34, v34
	v_mad_i64_i32 v[32:33], s[24:25], v145, s0, v[136:137]
	v_mul_f32_e32 v35, 0x45800000, v34
	v_cndmask_b32_e32 v34, v34, v35, vcc
	v_pk_mul_f32 v[28:29], v[28:29], v[34:35] op_sel_hi:[1,0]
	v_pk_mul_f32 v[30:31], v[30:31], v[34:35] op_sel_hi:[1,0]
	v_pk_mul_f32 v[26:27], v[26:27], v[34:35] op_sel_hi:[1,0]
	v_pk_mul_f32 v[24:25], v[24:25], v[34:35] op_sel_hi:[1,0]
	v_mul_f32_e32 v35, 0xbfb8aa3b, v28
	v_exp_f32_e32 v35, v35
	s_nop 0
	v_add_f32_e32 v35, 1.0, v35
	v_rcp_f32_e32 v36, v35
	v_mul_f32_e32 v35, 0xbfb8aa3b, v29
	v_exp_f32_e32 v35, v35
	s_nop 0
	v_add_f32_e32 v35, 1.0, v35
	v_rcp_f32_e32 v37, v35
; __device__ __forceinline__ unsigned cvt_pk_bf16(float lo, float hi) { f32x2 v = {lo, hi}; bf16x2_t b = __builtin_convertvector(v, bf16x2_t); return __builtin_bit_cast(unsigned, b); }
; __device__ __forceinline__ float silu_(float z) { return z * sigmoid_(z); }
; #define PG8_BAR __builtin_amdgcn_s_barrier()
; template <class Epi, class Sched, bool ALIGN_EPI = false, bool SP2 = false>
; __device__ __forceinline__ void gemm_phase(PG8_LAS unsigned char* lds, const Gemm g, const Sched& S, const Epi& E) {
;     ...
;         if (!has_next) break;
; #pragma unroll
;         for (int a = 0; a < 2; ++a)
; #pragma unroll
;             for (int b = 0; b < 2; ++b)
; #pragma unroll
;                 for (int m = 0; m < 4; ++m)
; #pragma unroll
;                     for (int n = 0; n < 2; ++n) acc[a][b][m][n] = (f32x4){0.f, 0.f, 0.f, 0.f};
;         cur = nxt; cA = nA; cB = nB; ++ui;
;         if constexpr (ALIGN_EPI) { if (wr == 1) PG8_BAR; }
;     __device__ __forceinline__ void operator()(const f32x4 (&acc)[2][2][4][2], const Unit& u, int wr, int wc, int fr, int fq) const {
;     ...
;             for (int m = 0; m < 4; ++m) { bf16_t* rowp = H + (size_t)(row0 + ai * HALF + m * 16) * DFF;
;                 const float rs = rsqrtf(rsv[ai][m] * (1.f / DM) + EPS);
; #pragma unroll
;                 for (int bj = 0; bj < 2; ++bj) { const f32x4 a = acc[ai][bj][m][0] * rs, g = acc[ai][bj][m][1] * rs;
;                     const int col = 16 * (8 * u.pn + 4 * bj + wc) + 4 * fq;
;                     u32x2 w; w.x = cvt_pk_bf16(silu_(a[0]) * g[0], silu_(a[1]) * g[1]); w.y = cvt_pk_bf16(silu_(a[2]) * g[2], silu_(a[3]) * g[3]);
;                     *(u32x2*)(rowp + col) = w; } }
	v_pk_mul_f32 v[20:21], v[20:21], v[34:35] op_sel_hi:[1,0]
	v_pk_mul_f32 v[16:17], v[16:17], v[34:35] op_sel_hi:[1,0]
	v_pk_mul_f32 v[22:23], v[22:23], v[34:35] op_sel_hi:[1,0]
	v_pk_mul_f32 v[28:29], v[28:29], v[36:37]
	v_pk_mul_f32 v[18:19], v[18:19], v[34:35] op_sel_hi:[1,0]
	v_pk_mul_f32 v[24:25], v[24:25], v[28:29]
	s_nop 0
	v_cvt_pk_bf16_f32 v24, v24, v25
	v_mul_f32_e32 v25, 0xbfb8aa3b, v30
	v_exp_f32_e32 v25, v25
	s_nop 0
	v_add_f32_e32 v25, 1.0, v25
	v_rcp_f32_e32 v28, v25
	v_mul_f32_e32 v25, 0xbfb8aa3b, v31
	v_exp_f32_e32 v25, v25
	s_nop 0
	v_add_f32_e32 v25, 1.0, v25
	v_rcp_f32_e32 v29, v25
	s_nop 0
	v_pk_mul_f32 v[28:29], v[30:31], v[28:29]
	s_nop 0
	v_pk_mul_f32 v[26:27], v[26:27], v[28:29]
	s_nop 0
	v_cvt_pk_bf16_f32 v25, v26, v27
	v_lshl_add_u64 v[26:27], v[32:33], 0, v[122:123]
	global_store_dwordx2 v[26:27], v[24:25], off
	v_mul_f32_e32 v24, 0xbfb8aa3b, v20
	v_mul_f32_e32 v25, 0xbfb8aa3b, v21
	v_exp_f32_e32 v24, v24
	v_exp_f32_e32 v25, v25
	v_add_f32_e32 v24, 1.0, v24
	v_add_f32_e32 v25, 1.0, v25
	v_rcp_f32_e32 v24, v24
	v_rcp_f32_e32 v25, v25
	s_nop 0
	v_pk_mul_f32 v[20:21], v[20:21], v[24:25]
	s_nop 0
	v_pk_mul_f32 v[16:17], v[16:17], v[20:21]
	s_nop 0
	v_cvt_pk_bf16_f32 v16, v16, v17
	v_mul_f32_e32 v17, 0xbfb8aa3b, v22
	v_exp_f32_e32 v17, v17
	s_nop 0
	v_add_f32_e32 v17, 1.0, v17
	v_rcp_f32_e32 v20, v17
	v_mul_f32_e32 v17, 0xbfb8aa3b, v23
	v_exp_f32_e32 v17, v17
	s_nop 0
	v_add_f32_e32 v17, 1.0, v17
	v_rcp_f32_e32 v21, v17
	s_nop 0
	v_pk_mul_f32 v[20:21], v[22:23], v[20:21]
	s_nop 0
	v_pk_mul_f32 v[18:19], v[18:19], v[20:21]
	s_nop 0
	v_cvt_pk_bf16_f32 v17, v18, v19
	v_fmamk_f32 v18, v142, 0x3a000000, v194
	v_cmp_gt_f32_e32 vcc, s33, v18
	v_mul_f32_e32 v19, 0x4b800000, v18
	global_store_dwordx2 v[26:27], v[16:17], off offset:128
	v_cndmask_b32_e32 v18, v18, v19, vcc
	v_rsq_f32_e32 v18, v18
	v_mad_i64_i32 v[16:17], s[24:25], v143, s0, v[136:137]
	s_mov_b64 s[24:25], -1
	v_mul_f32_e32 v19, 0x45800000, v18
	v_cndmask_b32_e32 v18, v18, v19, vcc
	v_pk_mul_f32 v[12:13], v[12:13], v[18:19] op_sel_hi:[1,0]
	v_pk_mul_f32 v[14:15], v[14:15], v[18:19] op_sel_hi:[1,0]
	v_pk_mul_f32 v[10:11], v[10:11], v[18:19] op_sel_hi:[1,0]
	v_pk_mul_f32 v[8:9], v[8:9], v[18:19] op_sel_hi:[1,0]
	v_mul_f32_e32 v19, 0xbfb8aa3b, v12
	v_exp_f32_e32 v19, v19
	s_andn2_b64 vcc, exec, s[6:7]
	v_add_f32_e32 v19, 1.0, v19
	v_rcp_f32_e32 v20, v19
	v_mul_f32_e32 v19, 0xbfb8aa3b, v13
	v_exp_f32_e32 v19, v19
	s_nop 0
	v_add_f32_e32 v19, 1.0, v19
	v_rcp_f32_e32 v21, v19
	v_pk_mul_f32 v[4:5], v[4:5], v[18:19] op_sel_hi:[1,0]
	v_pk_mul_f32 v[0:1], v[0:1], v[18:19] op_sel_hi:[1,0]
	v_pk_mul_f32 v[6:7], v[6:7], v[18:19] op_sel_hi:[1,0]
	v_pk_mul_f32 v[12:13], v[12:13], v[20:21]
	v_pk_mul_f32 v[2:3], v[2:3], v[18:19] op_sel_hi:[1,0]
	v_pk_mul_f32 v[8:9], v[8:9], v[12:13]
	s_nop 0
	v_cvt_pk_bf16_f32 v8, v8, v9
	v_mul_f32_e32 v9, 0xbfb8aa3b, v14
	v_exp_f32_e32 v9, v9
	s_nop 0
	v_add_f32_e32 v9, 1.0, v9
	v_rcp_f32_e32 v12, v9
	v_mul_f32_e32 v9, 0xbfb8aa3b, v15
	v_exp_f32_e32 v9, v9
	s_nop 0
	v_add_f32_e32 v9, 1.0, v9
	v_rcp_f32_e32 v13, v9
	s_nop 0
	v_pk_mul_f32 v[12:13], v[14:15], v[12:13]
	s_nop 0
	v_pk_mul_f32 v[10:11], v[10:11], v[12:13]
	s_nop 0
	v_cvt_pk_bf16_f32 v9, v10, v11
	v_lshl_add_u64 v[10:11], v[16:17], 0, v[122:123]
	global_store_dwordx2 v[10:11], v[8:9], off
	v_mul_f32_e32 v8, 0xbfb8aa3b, v4
	v_mul_f32_e32 v9, 0xbfb8aa3b, v5
	v_exp_f32_e32 v8, v8
	v_exp_f32_e32 v9, v9
	v_add_f32_e32 v8, 1.0, v8
	v_add_f32_e32 v9, 1.0, v9
	v_rcp_f32_e32 v8, v8
	v_rcp_f32_e32 v9, v9
	s_nop 0
	v_pk_mul_f32 v[4:5], v[4:5], v[8:9]
	s_nop 0
	v_pk_mul_f32 v[0:1], v[0:1], v[4:5]
	s_nop 0
	v_cvt_pk_bf16_f32 v0, v0, v1
	v_mul_f32_e32 v1, 0xbfb8aa3b, v6
	v_exp_f32_e32 v1, v1
	s_nop 0
	v_add_f32_e32 v1, 1.0, v1
	v_rcp_f32_e32 v4, v1
	v_mul_f32_e32 v1, 0xbfb8aa3b, v7
	v_exp_f32_e32 v1, v1
	s_nop 0
	v_add_f32_e32 v1, 1.0, v1
	v_rcp_f32_e32 v5, v1
	s_nop 0
	v_pk_mul_f32 v[4:5], v[6:7], v[4:5]
	s_nop 0
	v_pk_mul_f32 v[2:3], v[2:3], v[4:5]
	s_nop 0
	v_cvt_pk_bf16_f32 v1, v2, v3
	global_store_dwordx2 v[10:11], v[0:1], off offset:128
	s_cbranch_vccnz .LBB0_718
	s_andn2_b64 vcc, exec, s[8:9]
	s_cbranch_vccnz .LBB0_717
	s_barrier
	s_branch .LBB0_717
